# on top of v62: P0 positional-constant reduction on workgroups 0..31 issues its 128 loads as one batch and reduces after one wait instead of eight serial rounds
# baseline (speedup 1.0000x reference)
.LBB0_327:
	v_lshl_add_u64 v[18:19], v[8:9], 0, s[8:9]
	v_add_co_u32_e32 v20, vcc, 0x8000, v18
	global_load_dword v40, v[10:11], off offset:-1792
	global_load_dword v41, v[10:11], off offset:-1536
	global_load_dword v42, v[10:11], off offset:-1280
	global_load_dword v43, v[10:11], off offset:-1024
	global_load_dword v44, v[10:11], off offset:-768
	global_load_dword v45, v[10:11], off offset:-512
	global_load_dword v46, v[10:11], off offset:-256
	global_load_dword v47, v[10:11], off
	global_load_dword v48, v[18:19], off
	v_addc_co_u32_e32 v21, vcc, 0, v19, vcc
	v_add_co_u32_e32 v22, vcc, 0x10000, v18
	global_load_dword v49, v[20:21], off
	s_nop 0
	v_addc_co_u32_e32 v23, vcc, 0, v19, vcc
	v_add_co_u32_e32 v20, vcc, 0x18000, v18
	s_add_u32 s8, s8, 0x40000
	s_nop 0
	v_addc_co_u32_e32 v21, vcc, 0, v19, vcc
	v_add_co_u32_e32 v24, vcc, 0x20000, v18
	global_load_dword v50, v[22:23], off
	global_load_dword v51, v[20:21], off
	v_addc_co_u32_e32 v25, vcc, 0, v19, vcc
	v_add_co_u32_e32 v20, vcc, 0x28000, v18
	s_addc_u32 s9, s9, 0
	s_nop 0
	v_addc_co_u32_e32 v21, vcc, 0, v19, vcc
	v_add_co_u32_e32 v22, vcc, 0x30000, v18
	global_load_dword v52, v[24:25], off
	global_load_dword v53, v[20:21], off
	v_addc_co_u32_e32 v23, vcc, 0, v19, vcc
	v_add_co_u32_e32 v18, vcc, 0x38000, v18
	v_lshl_add_u64 v[10:11], v[10:11], 0, s[6:7]
	s_nop 0
	v_addc_co_u32_e32 v19, vcc, 0, v19, vcc
	global_load_dword v54, v[22:23], off
	global_load_dword v55, v[18:19], off
	v_lshl_add_u64 v[18:19], v[8:9], 0, s[8:9]
	v_add_co_u32_e32 v20, vcc, 0x8000, v18
	global_load_dword v56, v[10:11], off offset:-1792
	global_load_dword v57, v[10:11], off offset:-1536
	global_load_dword v58, v[10:11], off offset:-1280
	global_load_dword v59, v[10:11], off offset:-1024
	global_load_dword v60, v[10:11], off offset:-768
	global_load_dword v61, v[10:11], off offset:-512
	global_load_dword v62, v[10:11], off offset:-256
	global_load_dword v63, v[10:11], off
	global_load_dword v64, v[18:19], off
	v_addc_co_u32_e32 v21, vcc, 0, v19, vcc
	v_add_co_u32_e32 v22, vcc, 0x10000, v18
	global_load_dword v65, v[20:21], off
	s_nop 0
	v_addc_co_u32_e32 v23, vcc, 0, v19, vcc
	v_add_co_u32_e32 v20, vcc, 0x18000, v18
	s_add_u32 s8, s8, 0x40000
	s_nop 0
	v_addc_co_u32_e32 v21, vcc, 0, v19, vcc
	v_add_co_u32_e32 v24, vcc, 0x20000, v18
	global_load_dword v66, v[22:23], off
	global_load_dword v67, v[20:21], off
	v_addc_co_u32_e32 v25, vcc, 0, v19, vcc
	v_add_co_u32_e32 v20, vcc, 0x28000, v18
	s_addc_u32 s9, s9, 0
	s_nop 0
	v_addc_co_u32_e32 v21, vcc, 0, v19, vcc
	v_add_co_u32_e32 v22, vcc, 0x30000, v18
	global_load_dword v68, v[24:25], off
	global_load_dword v69, v[20:21], off
	v_addc_co_u32_e32 v23, vcc, 0, v19, vcc
	v_add_co_u32_e32 v18, vcc, 0x38000, v18
	v_lshl_add_u64 v[10:11], v[10:11], 0, s[6:7]
	s_nop 0
	v_addc_co_u32_e32 v19, vcc, 0, v19, vcc
	global_load_dword v70, v[22:23], off
	global_load_dword v71, v[18:19], off
	v_lshl_add_u64 v[18:19], v[8:9], 0, s[8:9]
	v_add_co_u32_e32 v20, vcc, 0x8000, v18
	global_load_dword v72, v[10:11], off offset:-1792
	global_load_dword v73, v[10:11], off offset:-1536
	global_load_dword v74, v[10:11], off offset:-1280
	global_load_dword v75, v[10:11], off offset:-1024
	global_load_dword v76, v[10:11], off offset:-768
	global_load_dword v77, v[10:11], off offset:-512
	global_load_dword v78, v[10:11], off offset:-256
	global_load_dword v79, v[10:11], off
	global_load_dword v80, v[18:19], off
	v_addc_co_u32_e32 v21, vcc, 0, v19, vcc
	v_add_co_u32_e32 v22, vcc, 0x10000, v18
	global_load_dword v81, v[20:21], off
	s_nop 0
	v_addc_co_u32_e32 v23, vcc, 0, v19, vcc
	v_add_co_u32_e32 v20, vcc, 0x18000, v18
	s_add_u32 s8, s8, 0x40000
	s_nop 0
	v_addc_co_u32_e32 v21, vcc, 0, v19, vcc
	v_add_co_u32_e32 v24, vcc, 0x20000, v18
	global_load_dword v82, v[22:23], off
	global_load_dword v83, v[20:21], off
	v_addc_co_u32_e32 v25, vcc, 0, v19, vcc
	v_add_co_u32_e32 v20, vcc, 0x28000, v18
	s_addc_u32 s9, s9, 0
	s_nop 0
	v_addc_co_u32_e32 v21, vcc, 0, v19, vcc
	v_add_co_u32_e32 v22, vcc, 0x30000, v18
	global_load_dword v84, v[24:25], off
	global_load_dword v85, v[20:21], off
	v_addc_co_u32_e32 v23, vcc, 0, v19, vcc
	v_add_co_u32_e32 v18, vcc, 0x38000, v18
	v_lshl_add_u64 v[10:11], v[10:11], 0, s[6:7]
	s_nop 0
	v_addc_co_u32_e32 v19, vcc, 0, v19, vcc
	global_load_dword v86, v[22:23], off
	global_load_dword v87, v[18:19], off
	v_lshl_add_u64 v[18:19], v[8:9], 0, s[8:9]
	v_add_co_u32_e32 v20, vcc, 0x8000, v18
	global_load_dword v88, v[10:11], off offset:-1792
	global_load_dword v89, v[10:11], off offset:-1536
	global_load_dword v90, v[10:11], off offset:-1280
	global_load_dword v91, v[10:11], off offset:-1024
	global_load_dword v92, v[10:11], off offset:-768
	global_load_dword v93, v[10:11], off offset:-512
	global_load_dword v94, v[10:11], off offset:-256
	global_load_dword v95, v[10:11], off
	global_load_dword v96, v[18:19], off
	v_addc_co_u32_e32 v21, vcc, 0, v19, vcc
	v_add_co_u32_e32 v22, vcc, 0x10000, v18
	global_load_dword v97, v[20:21], off
	s_nop 0
	v_addc_co_u32_e32 v23, vcc, 0, v19, vcc
	v_add_co_u32_e32 v20, vcc, 0x18000, v18
	s_add_u32 s8, s8, 0x40000
	s_nop 0
	v_addc_co_u32_e32 v21, vcc, 0, v19, vcc
	v_add_co_u32_e32 v24, vcc, 0x20000, v18
	global_load_dword v98, v[22:23], off
	global_load_dword v99, v[20:21], off
	v_addc_co_u32_e32 v25, vcc, 0, v19, vcc
	v_add_co_u32_e32 v20, vcc, 0x28000, v18
	s_addc_u32 s9, s9, 0
	s_nop 0
	v_addc_co_u32_e32 v21, vcc, 0, v19, vcc
	v_add_co_u32_e32 v22, vcc, 0x30000, v18
	global_load_dword v100, v[24:25], off
	global_load_dword v101, v[20:21], off
	v_addc_co_u32_e32 v23, vcc, 0, v19, vcc
	v_add_co_u32_e32 v18, vcc, 0x38000, v18
	v_lshl_add_u64 v[10:11], v[10:11], 0, s[6:7]
	s_nop 0
	v_addc_co_u32_e32 v19, vcc, 0, v19, vcc
	global_load_dword v102, v[22:23], off
	global_load_dword v103, v[18:19], off
	v_lshl_add_u64 v[18:19], v[8:9], 0, s[8:9]
	v_add_co_u32_e32 v20, vcc, 0x8000, v18
	global_load_dword v104, v[10:11], off offset:-1792
	global_load_dword v105, v[10:11], off offset:-1536
	global_load_dword v106, v[10:11], off offset:-1280
	global_load_dword v107, v[10:11], off offset:-1024
	global_load_dword v108, v[10:11], off offset:-768
	global_load_dword v109, v[10:11], off offset:-512
	global_load_dword v110, v[10:11], off offset:-256
	global_load_dword v111, v[10:11], off
	global_load_dword v112, v[18:19], off
	v_addc_co_u32_e32 v21, vcc, 0, v19, vcc
	v_add_co_u32_e32 v22, vcc, 0x10000, v18
	global_load_dword v113, v[20:21], off
	s_nop 0
	v_addc_co_u32_e32 v23, vcc, 0, v19, vcc
	v_add_co_u32_e32 v20, vcc, 0x18000, v18
	s_add_u32 s8, s8, 0x40000
	s_nop 0
	v_addc_co_u32_e32 v21, vcc, 0, v19, vcc
	v_add_co_u32_e32 v24, vcc, 0x20000, v18
	global_load_dword v114, v[22:23], off
	global_load_dword v115, v[20:21], off
	v_addc_co_u32_e32 v25, vcc, 0, v19, vcc
	v_add_co_u32_e32 v20, vcc, 0x28000, v18
	s_addc_u32 s9, s9, 0
	s_nop 0
	v_addc_co_u32_e32 v21, vcc, 0, v19, vcc
	v_add_co_u32_e32 v22, vcc, 0x30000, v18
	global_load_dword v116, v[24:25], off
	global_load_dword v117, v[20:21], off
	v_addc_co_u32_e32 v23, vcc, 0, v19, vcc
	v_add_co_u32_e32 v18, vcc, 0x38000, v18
	v_lshl_add_u64 v[10:11], v[10:11], 0, s[6:7]
	s_nop 0
	v_addc_co_u32_e32 v19, vcc, 0, v19, vcc
	global_load_dword v118, v[22:23], off
	global_load_dword v119, v[18:19], off
	v_lshl_add_u64 v[18:19], v[8:9], 0, s[8:9]
	v_add_co_u32_e32 v20, vcc, 0x8000, v18
	global_load_dword v120, v[10:11], off offset:-1792
	global_load_dword v121, v[10:11], off offset:-1536
	global_load_dword v122, v[10:11], off offset:-1280
	global_load_dword v123, v[10:11], off offset:-1024
	global_load_dword v124, v[10:11], off offset:-768
	global_load_dword v125, v[10:11], off offset:-512
	global_load_dword v126, v[10:11], off offset:-256
	global_load_dword v127, v[10:11], off
	global_load_dword v128, v[18:19], off
	v_addc_co_u32_e32 v21, vcc, 0, v19, vcc
	v_add_co_u32_e32 v22, vcc, 0x10000, v18
	global_load_dword v129, v[20:21], off
	s_nop 0
	v_addc_co_u32_e32 v23, vcc, 0, v19, vcc
	v_add_co_u32_e32 v20, vcc, 0x18000, v18
	s_add_u32 s8, s8, 0x40000
	s_nop 0
	v_addc_co_u32_e32 v21, vcc, 0, v19, vcc
	v_add_co_u32_e32 v24, vcc, 0x20000, v18
	global_load_dword v130, v[22:23], off
	global_load_dword v131, v[20:21], off
	v_addc_co_u32_e32 v25, vcc, 0, v19, vcc
	v_add_co_u32_e32 v20, vcc, 0x28000, v18
	s_addc_u32 s9, s9, 0
	s_nop 0
	v_addc_co_u32_e32 v21, vcc, 0, v19, vcc
	v_add_co_u32_e32 v22, vcc, 0x30000, v18
	global_load_dword v132, v[24:25], off
	global_load_dword v133, v[20:21], off
	v_addc_co_u32_e32 v23, vcc, 0, v19, vcc
	v_add_co_u32_e32 v18, vcc, 0x38000, v18
	v_lshl_add_u64 v[10:11], v[10:11], 0, s[6:7]
	s_nop 0
	v_addc_co_u32_e32 v19, vcc, 0, v19, vcc
	global_load_dword v134, v[22:23], off
	global_load_dword v135, v[18:19], off
	v_lshl_add_u64 v[18:19], v[8:9], 0, s[8:9]
	v_add_co_u32_e32 v20, vcc, 0x8000, v18
	global_load_dword v136, v[10:11], off offset:-1792
	global_load_dword v137, v[10:11], off offset:-1536
	global_load_dword v138, v[10:11], off offset:-1280
	global_load_dword v139, v[10:11], off offset:-1024
	global_load_dword v140, v[10:11], off offset:-768
	global_load_dword v141, v[10:11], off offset:-512
	global_load_dword v142, v[10:11], off offset:-256
	global_load_dword v143, v[10:11], off
	global_load_dword v144, v[18:19], off
	v_addc_co_u32_e32 v21, vcc, 0, v19, vcc
	v_add_co_u32_e32 v22, vcc, 0x10000, v18
	global_load_dword v145, v[20:21], off
	s_nop 0
	v_addc_co_u32_e32 v23, vcc, 0, v19, vcc
	v_add_co_u32_e32 v20, vcc, 0x18000, v18
	s_add_u32 s8, s8, 0x40000
	s_nop 0
	v_addc_co_u32_e32 v21, vcc, 0, v19, vcc
	v_add_co_u32_e32 v24, vcc, 0x20000, v18
	global_load_dword v146, v[22:23], off
	global_load_dword v147, v[20:21], off
	v_addc_co_u32_e32 v25, vcc, 0, v19, vcc
	v_add_co_u32_e32 v20, vcc, 0x28000, v18
	s_addc_u32 s9, s9, 0
	s_nop 0
	v_addc_co_u32_e32 v21, vcc, 0, v19, vcc
	v_add_co_u32_e32 v22, vcc, 0x30000, v18
	global_load_dword v148, v[24:25], off
	global_load_dword v149, v[20:21], off
	v_addc_co_u32_e32 v23, vcc, 0, v19, vcc
	v_add_co_u32_e32 v18, vcc, 0x38000, v18
	v_lshl_add_u64 v[10:11], v[10:11], 0, s[6:7]
	s_nop 0
	v_addc_co_u32_e32 v19, vcc, 0, v19, vcc
	global_load_dword v150, v[22:23], off
	global_load_dword v151, v[18:19], off
	v_lshl_add_u64 v[18:19], v[8:9], 0, s[8:9]
	v_add_co_u32_e32 v20, vcc, 0x8000, v18
	global_load_dword v152, v[10:11], off offset:-1792
	global_load_dword v153, v[10:11], off offset:-1536
	global_load_dword v154, v[10:11], off offset:-1280
	global_load_dword v155, v[10:11], off offset:-1024
	global_load_dword v156, v[10:11], off offset:-768
	global_load_dword v157, v[10:11], off offset:-512
	global_load_dword v158, v[10:11], off offset:-256
	global_load_dword v159, v[10:11], off
	global_load_dword v160, v[18:19], off
	v_addc_co_u32_e32 v21, vcc, 0, v19, vcc
	v_add_co_u32_e32 v22, vcc, 0x10000, v18
	global_load_dword v161, v[20:21], off
	s_nop 0
	v_addc_co_u32_e32 v23, vcc, 0, v19, vcc
	v_add_co_u32_e32 v20, vcc, 0x18000, v18
	s_add_u32 s8, s8, 0x40000
	s_nop 0
	v_addc_co_u32_e32 v21, vcc, 0, v19, vcc
	v_add_co_u32_e32 v24, vcc, 0x20000, v18
	global_load_dword v162, v[22:23], off
	global_load_dword v163, v[20:21], off
	v_addc_co_u32_e32 v25, vcc, 0, v19, vcc
	v_add_co_u32_e32 v20, vcc, 0x28000, v18
	s_addc_u32 s9, s9, 0
	s_nop 0
	v_addc_co_u32_e32 v21, vcc, 0, v19, vcc
	v_add_co_u32_e32 v22, vcc, 0x30000, v18
	global_load_dword v164, v[24:25], off
	global_load_dword v165, v[20:21], off
	v_addc_co_u32_e32 v23, vcc, 0, v19, vcc
	v_add_co_u32_e32 v18, vcc, 0x38000, v18
	v_lshl_add_u64 v[10:11], v[10:11], 0, s[6:7]
	s_nop 0
	v_addc_co_u32_e32 v19, vcc, 0, v19, vcc
	global_load_dword v166, v[22:23], off
	global_load_dword v167, v[18:19], off
	s_waitcnt vmcnt(0)
	v_fmac_f32_e32 v2, v40, v48
	v_fmac_f32_e32 v2, v41, v49
	v_fmac_f32_e32 v2, v42, v50
	v_fmac_f32_e32 v2, v43, v51
	v_fmac_f32_e32 v2, v44, v52
	v_fmac_f32_e32 v2, v45, v53
	v_fmac_f32_e32 v2, v46, v54
	v_fmac_f32_e32 v2, v47, v55
	v_fmac_f32_e32 v2, v56, v64
	v_fmac_f32_e32 v2, v57, v65
	v_fmac_f32_e32 v2, v58, v66
	v_fmac_f32_e32 v2, v59, v67
	v_fmac_f32_e32 v2, v60, v68
	v_fmac_f32_e32 v2, v61, v69
	v_fmac_f32_e32 v2, v62, v70
	v_fmac_f32_e32 v2, v63, v71
	v_fmac_f32_e32 v2, v72, v80
	v_fmac_f32_e32 v2, v73, v81
	v_fmac_f32_e32 v2, v74, v82
	v_fmac_f32_e32 v2, v75, v83
	v_fmac_f32_e32 v2, v76, v84
	v_fmac_f32_e32 v2, v77, v85
	v_fmac_f32_e32 v2, v78, v86
	v_fmac_f32_e32 v2, v79, v87
	v_fmac_f32_e32 v2, v88, v96
	v_fmac_f32_e32 v2, v89, v97
	v_fmac_f32_e32 v2, v90, v98
	v_fmac_f32_e32 v2, v91, v99
	v_fmac_f32_e32 v2, v92, v100
	v_fmac_f32_e32 v2, v93, v101
	v_fmac_f32_e32 v2, v94, v102
	v_fmac_f32_e32 v2, v95, v103
	v_fmac_f32_e32 v2, v104, v112
	v_fmac_f32_e32 v2, v105, v113
	v_fmac_f32_e32 v2, v106, v114
	v_fmac_f32_e32 v2, v107, v115
	v_fmac_f32_e32 v2, v108, v116
	v_fmac_f32_e32 v2, v109, v117
	v_fmac_f32_e32 v2, v110, v118
	v_fmac_f32_e32 v2, v111, v119
	v_fmac_f32_e32 v2, v120, v128
	v_fmac_f32_e32 v2, v121, v129
	v_fmac_f32_e32 v2, v122, v130
	v_fmac_f32_e32 v2, v123, v131
	v_fmac_f32_e32 v2, v124, v132
	v_fmac_f32_e32 v2, v125, v133
	v_fmac_f32_e32 v2, v126, v134
	v_fmac_f32_e32 v2, v127, v135
	v_fmac_f32_e32 v2, v136, v144
	v_fmac_f32_e32 v2, v137, v145
	v_fmac_f32_e32 v2, v138, v146
	v_fmac_f32_e32 v2, v139, v147
	v_fmac_f32_e32 v2, v140, v148
	v_fmac_f32_e32 v2, v141, v149
	v_fmac_f32_e32 v2, v142, v150
	v_fmac_f32_e32 v2, v143, v151
	v_fmac_f32_e32 v2, v152, v160
	v_fmac_f32_e32 v2, v153, v161
	v_fmac_f32_e32 v2, v154, v162
	v_fmac_f32_e32 v2, v155, v163
	v_fmac_f32_e32 v2, v156, v164
	v_fmac_f32_e32 v2, v157, v165
	v_fmac_f32_e32 v2, v158, v166
	v_fmac_f32_e32 v2, v159, v167
	ds_bpermute_b32 v8, v1, v2
	s_waitcnt lgkmcnt(0)
	v_add_f32_e32 v2, v2, v8
	ds_bpermute_b32 v8, v12, v2
	s_waitcnt lgkmcnt(0)
	v_add_f32_e32 v2, v2, v8
	ds_bpermute_b32 v8, v13, v2
	s_waitcnt lgkmcnt(0)
	v_add_f32_e32 v2, v2, v8
	ds_bpermute_b32 v8, v14, v2
	s_waitcnt lgkmcnt(0)
	v_add_f32_e32 v2, v2, v8
	ds_bpermute_b32 v8, v15, v2
	s_waitcnt lgkmcnt(0)
	v_add_f32_e32 v2, v2, v8
	ds_bpermute_b32 v8, v16, v2
	s_and_saveexec_b64 s[8:9], s[4:5]
	s_cbranch_execz .LBB0_325
	s_ashr_i32 s1, s0, 31
	s_lshl_b64 s[12:13], s[0:1], 2
	s_add_u32 s12, s10, s12
	s_waitcnt lgkmcnt(0)
	v_add_f32_e32 v2, v2, v8
	s_addc_u32 s13, s11, s13
	global_store_dword v3, v2, s[12:13]
	s_branch .LBB0_325
